# ffn_fix: each of the four workgroups of an M-block fixes a quarter of its edge rows and the four meet at a counter, instead of all four doing the whole fix
# speedup vs baseline: 1.0053x; 1.0010x over previous
; __global__ void __launch_bounds__(512, 2) mega(Params P0) {
;     ...
;     for (int ph = ph_lo; ph <= ph_hi; ++ph) {
;         int tid = threadIdx.x; asm volatile("" : "+v"(tid));
;         int G = gridDim.x, bid = blockIdx.x; asm volatile("" : "+s"(G)); asm volatile("" : "+s"(bid));
;         KArgP kp = (KArgP)__builtin_amdgcn_kernarg_segment_ptr(); asm volatile("" : "+s"(kp));
;         Params P;
; #pragma unroll
;         for (int i = 0; i < 24; ++i) P.in[i] = kp->in[i];
;         P.out = kp->out; P.ws = kp->ws; P.ph_lo = 0; P.ph_hi = 0;
;         unsigned char* dob = (unsigned char*)P.out; unsigned char* ws = P.ws;
;         if (ph == 0) phase0(P, lds, G, bid);
;         else if (ph == 1) { pg8::Gemm g{(const bf16_t*)(dob + DO_ABF), (const bf16_t*)(dob + DO_W1T), NTOK, NPROJ, DM}; pg8::StaticOrder S; S.init(NTOK, NPROJ, G, bid);
;             EpiProj E{(bf16_t*)(ws + WS_PROJ), (const f32x2*)(dob + DO_ROPE), (bf16_t*)(dob + DO_HQ), P.in[6], P.in[7]}; pg8::gemm_phase(lds, g, S, E); }
;         else if (ph == 2) phase_conv(P, G, bid);
;         else if (ph == 3) phase_mix1(P, lds, G, bid);
;         else if (ph == 4) phase_mix2(P, lds, G, bid);
;         else if (ph == 5) {
;             { float* r2 = (float*)(ws + WS_RSS2); for (int i = bid * 512 + tid; i < 2 * NTOK; i += G * 512) r2[i] = 0.f;
;               if (bid == 0 && tid == 0) __hip_atomic_store((unsigned*)(ws + WS_BAR), 0u, __ATOMIC_RELAXED, __HIP_MEMORY_SCOPE_AGENT); }
.LBB0_10:
	v_readlane_b32 s2, v253, 0
	v_mov_b32_e32 v186, v162
	s_mov_b32 s89, s82
	s_mov_b32 s77, s88
	v_readlane_b32 s3, v253, 1
	s_load_dwordx16 s[4:19], s[2:3], 0x0
	s_load_dwordx4 s[20:23], s[2:3], 0xc0
	s_mov_b64 s[56:57], 0
	s_cmp_lt_i32 s80, 3
	s_mov_b64 s[90:91], 0
	s_waitcnt lgkmcnt(0)
	v_writelane_b32 v254, s4, 34
	s_nop 1
	v_writelane_b32 v254, s5, 35
	v_writelane_b32 v254, s6, 36
	v_writelane_b32 v254, s7, 37
	v_writelane_b32 v254, s8, 38
	v_writelane_b32 v254, s9, 39
	v_writelane_b32 v254, s10, 40
	v_writelane_b32 v254, s11, 41
	v_writelane_b32 v254, s12, 42
	v_writelane_b32 v254, s13, 43
	v_writelane_b32 v254, s14, 44
	v_writelane_b32 v254, s15, 45
	v_writelane_b32 v254, s16, 46
	v_writelane_b32 v254, s17, 47
	v_writelane_b32 v254, s18, 48
	v_writelane_b32 v254, s19, 49
	s_load_dwordx16 s[4:19], s[2:3], 0x40
	s_waitcnt lgkmcnt(0)
	v_writelane_b32 v254, s4, 50
	s_nop 1
	v_writelane_b32 v254, s5, 51
	v_writelane_b32 v254, s6, 52
	v_writelane_b32 v254, s7, 53
	v_writelane_b32 v254, s8, 54
	v_writelane_b32 v254, s9, 55
	v_writelane_b32 v254, s10, 56
	v_writelane_b32 v254, s11, 57
	v_writelane_b32 v254, s12, 58
	v_writelane_b32 v254, s13, 59
	v_writelane_b32 v254, s14, 60
	v_writelane_b32 v254, s15, 61
	v_writelane_b32 v254, s16, 62
	v_writelane_b32 v255, s18, 0
	v_writelane_b32 v254, s17, 63
	v_writelane_b32 v255, s19, 1
	s_load_dwordx16 s[4:19], s[2:3], 0x80
	s_mov_b64 s[2:3], -1
	s_waitcnt lgkmcnt(0)
	v_writelane_b32 v255, s4, 2
	s_nop 1
	v_writelane_b32 v255, s5, 3
	v_writelane_b32 v255, s6, 4
	v_writelane_b32 v255, s7, 5
	v_writelane_b32 v255, s8, 6
	v_writelane_b32 v255, s9, 7
	v_writelane_b32 v255, s10, 8
	v_writelane_b32 v255, s11, 9
	v_writelane_b32 v255, s12, 10
	v_writelane_b32 v255, s13, 11
	v_writelane_b32 v255, s14, 12
	v_writelane_b32 v255, s15, 13
	v_writelane_b32 v255, s16, 14
	v_writelane_b32 v255, s17, 15
	v_writelane_b32 v255, s18, 16
	v_writelane_b32 v255, s19, 17
	v_writelane_b32 v255, s89, 18
	v_writelane_b32 v255, s77, 19
	s_cbranch_scc1 .LBB0_573
	s_cmp_gt_i32 s80, 3
	s_cbranch_scc0 .LBB0_372
	s_cmp_gt_i32 s80, 4
	v_writelane_b32 v255, s80, 20
	s_nop 1
	v_writelane_b32 v255, s81, 21
	v_writelane_b32 v255, s82, 22
	v_writelane_b32 v255, s83, 23
	s_cbranch_scc0 .LBB0_69
	s_cmp_eq_u32 s80, 5
	s_mov_b64 s[90:91], -1
	s_cbranch_scc0 .LBB0_68
	s_cmp_lg_u32 s77, 0
	s_cbranch_scc1 .Lpgz_skip
	v_cmp_gt_u32_e32 vcc, 0x100, v186
	s_and_saveexec_b64 s[2:3], vcc
	v_lshlrev_b32_e32 v2, 2, v186
	v_mov_b32_e32 v3, 0
	s_add_u32 s6, s22, 0xd340000
	s_addc_u32 s7, s23, 0
	global_store_dword v2, v3, s[6:7]
	s_or_b64 exec, exec, s[2:3]

; __device__ void ffn_fix(bf16_t* ACT, const bf16_t* GR, const bf16_t* UP, const float* cw, const float* cb, int pm, int half) {
;     ...
;     asm volatile("s_waitcnt vmcnt(0)" ::: "memory"); __syncthreads();
; }
.LBB0_804:
	s_or_b64 exec, exec, s[8:9]
	s_waitcnt vmcnt(0)
	s_mov_b32 s12, s26
	s_waitcnt vmcnt(0)
	s_barrier
	s_lshl_b32 s13, s26, 2
	s_add_u32 s10, s22, 0xd340200
	s_addc_u32 s11, s23, 0
	s_add_u32 s10, s10, s13
	s_addc_u32 s11, s11, 0
	v_cmp_eq_u32_e32 vcc, 0, v162
	s_and_saveexec_b64 s[8:9], vcc
	s_cbranch_execz .Lfx_met
	v_mov_b32_e32 v0, 0
	v_mov_b32_e32 v2, 1
	global_atomic_add v3, v0, v2, s[10:11] sc0
	s_waitcnt vmcnt(0)
	v_readfirstlane_b32 s17, v3
	s_nop 3
	s_and_b32 s17, s17, -4
	s_add_i32 s17, s17, 4
	s_mov_b32 s13, 0
.Lfx_spin:
	global_load_dword v3, v0, s[10:11] sc1
	s_waitcnt vmcnt(0)
	v_readfirstlane_b32 s18, v3
	s_nop 3
	s_cmp_ge_u32 s18, s17
	s_cbranch_scc1 .Lfx_met
	s_sleep 1
	s_add_i32 s13, s13, 1
	s_cmp_lt_u32 s13, 0x4000
	s_cbranch_scc1 .Lfx_spin
.Lfx_met:
	s_or_b64 exec, exec, s[8:9]
	s_barrier

; __device__ __forceinline__ float bf_lo(unsigned w) { return __uint_as_float(w << 16); }
; __device__ __forceinline__ float bf_hi(unsigned w) { return __uint_as_float(w & 0xffff0000u); }
; __device__ void ffn_fix(bf16_t* ACT, const bf16_t* GR, const bf16_t* UP, const float* cw, const float* cb, int pm, int half) {
;     ...
;     const int seqgroups = half ? 32 : 128;
;     for (int it = tid; it < 8 * 352; it += 512) { const int br = it / 352, col = (it % 352) * 8; const int group = pm * 4 + (br >> 1), which = br & 1;
;         const bool seq_first = (group % seqgroups) == 0, seq_last = (group % seqgroups) == seqgroups - 1;
;         const bf16_t* pp = which ? GR + (size_t)(group * 4 + 2) * DFF : GR + (size_t)((seq_first ? group : group - 1) * 4 + 3) * DFF;
;         const bf16_t* pc = GR + (size_t)(group * 4 + (which ? 3 : 0)) * DFF;
;         const bf16_t* pn = which ? GR + (size_t)((seq_last ? group : group + 1) * 4 + 0) * DFF : GR + (size_t)(group * 4 + 1) * DFF;
;         const float mp = (!which && seq_first) ? 0.f : 1.f, mn = (which && seq_last) ? 0.f : 1.f;
;         const u32x4 gp = *(const u32x4*)(pp + col), gc = *(const u32x4*)(pc + col), gn = *(const u32x4*)(pn + col), up = *(const u32x4*)(UP + (size_t)(group * 2 + which) * DFF + col);
;         u32x4 ov;
; #pragma unroll
;         for (int q = 0; q < 4; ++q) { const int c = col + 2 * q;
;             const float u0 = bf_lo(gp[q]) * mp * cw[c] + bf_lo(gc[q]) * cw[DFF + c] + bf_lo(gn[q]) * mn * cw[2 * DFF + c] + cb[c];
;             const float u1 = bf_hi(gp[q]) * mp * cw[c + 1] + bf_hi(gc[q]) * cw[DFF + c + 1] + bf_hi(gn[q]) * mn * cw[2 * DFF + c + 1] + cb[c + 1];
.LBB0_813:
	v_mov_b64_e32 v[2:3], 0x100
	s_nop 0
	v_cmp_lt_i64_e32 vcc, s[8:9], v[2:3]
	s_mov_b64 s[8:9], -1
	s_cbranch_vccz .LBB0_806
	s_cmp_eq_u32 s26, s12
	s_cbranch_scc1 .LBB0_805
	s_lshr_b32 s8, s77, 6
	s_mul_i32 s8, s8, 0x2c0
	v_add_u32_e32 v33, s8, v162
	s_addk_i32 s8, 0x2c0
	s_nop 0
	v_cmp_gt_i32_e32 vcc, s8, v33
	s_and_saveexec_b64 s[8:9], vcc
	s_cbranch_execz .LBB0_804
	s_lshl_b32 s17, s26, 2
	v_lshlrev_b32_e32 v32, 3, v33
	s_mov_b64 s[10:11], 0
	s_branch .LBB0_818
.LBB0_817:
	s_or_b64 exec, exec, s[12:13]
	v_mul_i32_i24_e32 v3, 0x160, v3
	v_lshlrev_b32_e32 v3, 3, v3
	v_sub_u32_e32 v22, v32, v3
	v_mov_b64_e32 v[10:11], s[4:5]
	s_movk_i32 s18, 0x1600
	v_ashrrev_i32_e32 v23, 31, v22
	v_mad_i64_i32 v[12:13], s[12:13], v5, s18, v[10:11]
	v_lshlrev_b64 v[18:19], 1, v[22:23]
	v_or_b32_e32 v4, v6, v4
	v_mad_i64_i32 v[6:7], s[12:13], v8, s18, v[10:11]
	v_lshl_add_u64 v[8:9], v[12:13], 0, v[18:19]
	v_mad_i64_i32 v[4:5], s[12:13], v4, s18, v[10:11]
	global_load_dwordx4 v[10:13], v[8:9], off
	v_readlane_b32 s60, v255, 2
	v_readlane_b32 s61, v255, 3
	v_lshl_add_u64 v[4:5], v[4:5], 0, v[18:19]
	v_lshlrev_b64 v[22:23], 2, v[22:23]
	v_readlane_b32 s62, v255, 4
	v_readlane_b32 s63, v255, 5
	s_mov_b64 s[40:41], s[60:61]
	global_load_dwordx4 v[14:17], v[4:5], off
	v_lshl_add_u64 v[24:25], s[40:41], 0, v[22:23]
	v_lshl_add_u64 v[4:5], v[6:7], 0, v[18:19]
	global_load_dwordx2 v[30:31], v[24:25], off
	global_load_dwordx4 v[6:9], v[4:5], off
	s_mov_b64 s[42:43], s[62:63]
	v_lshl_add_u64 v[22:23], s[42:43], 0, v[22:23]
	v_lshl_or_b32 v4, v34, 1, v2
	v_mov_b64_e32 v[2:3], s[6:7]
	s_nop 0
	v_mad_i64_i32 v[2:3], s[12:13], v4, s18, v[2:3]
	v_lshl_add_u64 v[2:3], v[2:3], 0, v[18:19]
	global_load_dwordx4 v[2:5], v[2:3], off
	v_add_co_u32_e32 v76, vcc, 0x2c00, v24
	s_nop 1
	v_addc_co_u32_e32 v77, vcc, 0, v25, vcc
	v_add_co_u32_e32 v78, vcc, 0x5800, v24
	s_nop 1
	v_addc_co_u32_e32 v79, vcc, 0, v25, vcc
	global_load_dwordx4 v[44:47], v[24:25], off
	global_load_dwordx4 v[48:51], v[24:25], off offset:16
	global_load_dwordx4 v[52:55], v[76:77], off
	global_load_dwordx4 v[56:59], v[76:77], off offset:16
	global_load_dwordx4 v[60:63], v[78:79], off
	global_load_dwordx4 v[64:67], v[78:79], off offset:16
	global_load_dwordx4 v[68:71], v[22:23], off
	global_load_dwordx4 v[72:75], v[22:23], off offset:16
	s_mov_b32 s12, 0xbf3a00e3
	s_mov_b32 s34, 0x3f35f0e3
	s_mov_b32 s36, 0xbe11a98e
	s_mov_b32 s38, 0x3e027906
	s_mov_b32 s40, 0xbf38aa3b
	v_add_u32_e32 v32, 0x1000, v32
	v_readlane_b32 s64, v255, 6
	v_readlane_b32 s65, v255, 7
	v_readlane_b32 s66, v255, 8
	v_readlane_b32 s67, v255, 9
	v_readlane_b32 s68, v255, 10
	v_readlane_b32 s69, v255, 11
	v_readlane_b32 s70, v255, 12
	v_readlane_b32 s71, v255, 13
	v_readlane_b32 s72, v255, 14
	v_readlane_b32 s73, v255, 15
	v_readlane_b32 s74, v255, 16
	v_readlane_b32 s75, v255, 17
	s_waitcnt vmcnt(0)
	v_lshlrev_b32_e32 v26, 16, v10
	v_and_b32_e32 v27, 0xffff0000, v10
	v_pk_mul_f32 v[28:29], v[20:21], v[26:27] op_sel_hi:[0,1]
	v_add_co_u32_e32 v26, vcc, s83, v24
	v_lshlrev_b32_e32 v36, 16, v14
	s_nop 0
	v_addc_co_u32_e32 v27, vcc, 0, v25, vcc
	v_mov_b64_e32 v[38:39], v[52:53]
	v_and_b32_e32 v37, 0xffff0000, v14
	v_lshlrev_b32_e32 v14, 16, v2
	v_and_b32_e32 v2, 0xffff0000, v2
	s_waitcnt vmcnt(0)
	v_pk_mul_f32 v[36:37], v[38:39], v[36:37]
	s_nop 0
	v_pk_fma_f32 v[30:31], v[28:29], v[30:31], v[36:37]
	v_lshlrev_b32_e32 v28, 16, v6
	v_and_b32_e32 v29, 0xffff0000, v6
	v_pk_mul_f32 v[36:37], v[0:1], v[28:29] op_sel_hi:[0,1]
	v_add_co_u32_e32 v28, vcc, s28, v24
	s_nop 1
	v_addc_co_u32_e32 v29, vcc, 0, v25, vcc
	v_mov_b64_e32 v[38:39], v[60:61]
	s_waitcnt vmcnt(0)
	v_pk_fma_f32 v[30:31], v[36:37], v[38:39], v[30:31]
	v_mov_b64_e32 v[36:37], v[68:69]
	s_waitcnt vmcnt(0)
	v_pk_add_f32 v[36:37], v[36:37], v[30:31]
	s_nop 0
	v_and_b32_e32 v31, 0x7fffffff, v37
	v_and_b32_e32 v30, 0x7fffffff, v36
	v_pk_fma_f32 v[30:31], v[30:31], s[54:55], 1.0 op_sel_hi:[1,0,0]
	v_cmp_gt_f32_e32 vcc, 0, v36
	v_rcp_f32_e32 v38, v30
	v_rcp_f32_e32 v39, v31
	v_mov_b64_e32 v[30:31], s[12:13]
	s_mov_b32 s12, 0x3f07dc22
	v_pk_fma_f32 v[40:41], v[38:39], s[12:13], v[30:31] op_sel_hi:[1,0,0]
	s_nop 0
	v_pk_fma_f32 v[40:41], v[38:39], v[40:41], s[34:35] op_sel_hi:[1,1,0]
	s_nop 0
	v_pk_fma_f32 v[40:41], v[38:39], v[40:41], s[36:37] op_sel_hi:[1,1,0]
	s_nop 0
	v_pk_fma_f32 v[40:41], v[38:39], v[40:41], s[38:39] op_sel_hi:[1,1,0]
	s_nop 0
	v_pk_mul_f32 v[38:39], v[38:39], v[40:41]
	v_pk_mul_f32 v[40:41], v[36:37], v[36:37]
	s_nop 0
	v_pk_mul_f32 v[40:41], v[40:41], s[40:41] op_sel_hi:[1,0]
	s_nop 0
	v_exp_f32_e32 v40, v40
	v_exp_f32_e32 v41, v41
	s_nop 0
	v_pk_mul_f32 v[38:39], v[40:41], v[38:39]
	s_nop 0
	v_pk_mul_f32 v[40:41], v[36:37], v[38:39]
	v_pk_fma_f32 v[38:39], v[36:37], v[38:39], v[36:37] neg_lo:[1,0,0] neg_hi:[1,0,0]
	s_nop 0
	v_cndmask_b32_e32 v6, v38, v40, vcc
	v_cmp_gt_f32_e32 vcc, 0, v37
	v_mul_f32_e32 v6, v6, v14
	v_lshlrev_b32_e32 v14, 16, v15
	v_cndmask_b32_e32 v10, v39, v41, vcc
	v_mul_f32_e32 v2, v10, v2
	v_cvt_pk_bf16_f32 v2, v6, v2
	v_mov_b64_e32 v[36:37], v[46:47]
	v_mov_b64_e32 v[38:39], v[54:55]
	v_lshlrev_b32_e32 v10, 16, v11
	v_and_b32_e32 v11, 0xffff0000, v11
	v_and_b32_e32 v15, 0xffff0000, v15
	v_pk_mul_f32 v[10:11], v[20:21], v[10:11] op_sel_hi:[0,1]
	v_lshlrev_b32_e32 v6, 16, v7
	v_and_b32_e32 v7, 0xffff0000, v7
	v_pk_mul_f32 v[6:7], v[0:1], v[6:7] op_sel_hi:[0,1]
	s_waitcnt vmcnt(0)
	v_pk_mul_f32 v[14:15], v[38:39], v[14:15]
	s_nop 0
	v_pk_fma_f32 v[10:11], v[10:11], v[36:37], v[14:15]
	v_mov_b64_e32 v[14:15], v[62:63]
	s_waitcnt vmcnt(0)
; __device__ __forceinline__ unsigned cvt_pk_bf16(float lo, float hi) { unsigned r; asm volatile("v_cvt_pk_bf16_f32 %0, %1, %2" : "=v"(r) : "v"(lo), "v"(hi)); return r; }
; __device__ __forceinline__ float bf_lo(unsigned w) { return __uint_as_float(w << 16); }
; __device__ __forceinline__ float bf_hi(unsigned w) { return __uint_as_float(w & 0xffff0000u); }
; __device__ void ffn_fix(bf16_t* ACT, const bf16_t* GR, const bf16_t* UP, const float* cw, const float* cb, int pm, int half) {
;     ...
;             const float u0 = bf_lo(gp[q]) * mp * cw[c] + bf_lo(gc[q]) * cw[DFF + c] + bf_lo(gn[q]) * mn * cw[2 * DFF + c] + cb[c];
;             const float u1 = bf_hi(gp[q]) * mp * cw[c + 1] + bf_hi(gc[q]) * cw[DFF + c + 1] + bf_hi(gn[q]) * mn * cw[2 * DFF + c + 1] + cb[c + 1];
;             const f32x2 ge = gelu_pk((f32x2){u0, u1}); ov[q] = cvt_pk_bf16(ge.x * bf_lo(up[q]), ge.y * bf_hi(up[q])); }
;         *(u32x4*)(ACT + (size_t)(group * 64 + (which ? 63 : 0)) * DFF + col) = ov; }
	v_pk_fma_f32 v[6:7], v[6:7], v[14:15], v[10:11]
	v_mov_b64_e32 v[10:11], v[70:71]
	s_waitcnt vmcnt(0)
	v_pk_add_f32 v[6:7], v[10:11], v[6:7]
	s_nop 0
	v_and_b32_e32 v11, 0x7fffffff, v7
	v_and_b32_e32 v10, 0x7fffffff, v6
	v_pk_fma_f32 v[10:11], v[10:11], s[54:55], 1.0 op_sel_hi:[1,0,0]
	v_cmp_gt_f32_e32 vcc, 0, v6
	v_rcp_f32_e32 v10, v10
	v_rcp_f32_e32 v11, v11
	s_nop 0
	v_pk_fma_f32 v[14:15], v[10:11], s[12:13], v[30:31] op_sel_hi:[1,0,0]
	s_nop 0
	v_pk_fma_f32 v[14:15], v[10:11], v[14:15], s[34:35] op_sel_hi:[1,1,0]
	s_nop 0
	v_pk_fma_f32 v[14:15], v[10:11], v[14:15], s[36:37] op_sel_hi:[1,1,0]
	s_nop 0
	v_pk_fma_f32 v[14:15], v[10:11], v[14:15], s[38:39] op_sel_hi:[1,1,0]
	s_nop 0
	v_pk_mul_f32 v[10:11], v[10:11], v[14:15]
	v_pk_mul_f32 v[14:15], v[6:7], v[6:7]
	s_nop 0
	v_pk_mul_f32 v[14:15], v[14:15], s[40:41] op_sel_hi:[1,0]
	s_nop 0
	v_exp_f32_e32 v14, v14
	v_exp_f32_e32 v15, v15
	s_nop 0
	v_pk_mul_f32 v[10:11], v[14:15], v[10:11]
	s_nop 0
	v_pk_mul_f32 v[14:15], v[6:7], v[10:11]
	v_pk_fma_f32 v[10:11], v[6:7], v[10:11], v[6:7] neg_lo:[1,0,0] neg_hi:[1,0,0]
	s_nop 0
	v_cndmask_b32_e32 v6, v10, v14, vcc
	v_cmp_gt_f32_e32 vcc, 0, v7
	v_lshlrev_b32_e32 v10, 16, v3
	v_and_b32_e32 v3, 0xffff0000, v3
	v_cndmask_b32_e32 v7, v11, v15, vcc
	v_mul_f32_e32 v3, v7, v3
	v_mul_f32_e32 v6, v6, v10
	v_cvt_pk_bf16_f32 v3, v6, v3
	v_mov_b64_e32 v[10:11], v[48:49]
	v_mov_b64_e32 v[36:37], v[56:57]
	v_lshlrev_b32_e32 v6, 16, v12
	v_and_b32_e32 v7, 0xffff0000, v12
	v_lshlrev_b32_e32 v14, 16, v16
	v_and_b32_e32 v15, 0xffff0000, v16
	v_pk_mul_f32 v[6:7], v[20:21], v[6:7] op_sel_hi:[0,1]
	v_lshlrev_b32_e32 v12, 16, v17
	s_waitcnt vmcnt(0)
	v_pk_mul_f32 v[14:15], v[36:37], v[14:15]
	s_nop 0
	v_pk_fma_f32 v[6:7], v[6:7], v[10:11], v[14:15]
	v_mov_b64_e32 v[14:15], v[64:65]
	v_lshlrev_b32_e32 v10, 16, v8
	v_and_b32_e32 v11, 0xffff0000, v8
	v_pk_mul_f32 v[10:11], v[0:1], v[10:11] op_sel_hi:[0,1]
	v_lshlrev_b32_e32 v8, 16, v4
	v_and_b32_e32 v4, 0xffff0000, v4
	s_waitcnt vmcnt(0)
	v_pk_fma_f32 v[6:7], v[10:11], v[14:15], v[6:7]
	v_mov_b64_e32 v[10:11], v[72:73]
	s_waitcnt vmcnt(0)
	v_pk_add_f32 v[6:7], v[10:11], v[6:7]
	s_nop 0
	v_and_b32_e32 v11, 0x7fffffff, v7
	v_and_b32_e32 v10, 0x7fffffff, v6
	v_pk_fma_f32 v[10:11], v[10:11], s[54:55], 1.0 op_sel_hi:[1,0,0]
	v_cmp_gt_f32_e32 vcc, 0, v6
	v_rcp_f32_e32 v10, v10
	v_rcp_f32_e32 v11, v11
	s_nop 0
	v_pk_fma_f32 v[14:15], v[10:11], s[12:13], v[30:31] op_sel_hi:[1,0,0]
	s_nop 0
	v_pk_fma_f32 v[14:15], v[10:11], v[14:15], s[34:35] op_sel_hi:[1,1,0]
	s_nop 0
	v_pk_fma_f32 v[14:15], v[10:11], v[14:15], s[36:37] op_sel_hi:[1,1,0]
	s_nop 0
	v_pk_fma_f32 v[14:15], v[10:11], v[14:15], s[38:39] op_sel_hi:[1,1,0]
	s_nop 0
	v_pk_mul_f32 v[10:11], v[10:11], v[14:15]
	v_pk_mul_f32 v[14:15], v[6:7], v[6:7]
	s_nop 0
	v_pk_mul_f32 v[14:15], v[14:15], s[40:41] op_sel_hi:[1,0]
	s_nop 0
	v_exp_f32_e32 v14, v14
	v_exp_f32_e32 v15, v15
	s_nop 0
	v_pk_mul_f32 v[10:11], v[14:15], v[10:11]
	s_nop 0
	v_pk_mul_f32 v[14:15], v[6:7], v[10:11]
	v_pk_fma_f32 v[10:11], v[6:7], v[10:11], v[6:7] neg_lo:[1,0,0] neg_hi:[1,0,0]
	s_nop 0
	v_cndmask_b32_e32 v6, v10, v14, vcc
	v_cmp_gt_f32_e32 vcc, 0, v7
	v_mul_f32_e32 v6, v6, v8
	v_lshlrev_b32_e32 v8, 16, v9
	v_cndmask_b32_e32 v7, v11, v15, vcc
	v_mul_f32_e32 v4, v7, v4
	v_cvt_pk_bf16_f32 v4, v6, v4
	v_mov_b64_e32 v[10:11], v[50:51]
	v_mov_b64_e32 v[14:15], v[58:59]
	v_lshlrev_b32_e32 v6, 16, v13
	v_and_b32_e32 v7, 0xffff0000, v13
	v_and_b32_e32 v13, 0xffff0000, v17
	v_pk_mul_f32 v[6:7], v[20:21], v[6:7] op_sel_hi:[0,1]
	v_and_b32_e32 v9, 0xffff0000, v9
	v_pk_mul_f32 v[8:9], v[0:1], v[8:9] op_sel_hi:[0,1]
	s_waitcnt vmcnt(0)
	v_pk_mul_f32 v[12:13], v[14:15], v[12:13]
	s_nop 0
	v_pk_fma_f32 v[6:7], v[6:7], v[10:11], v[12:13]
	v_mov_b64_e32 v[10:11], v[66:67]
	s_waitcnt vmcnt(0)
	v_pk_fma_f32 v[6:7], v[8:9], v[10:11], v[6:7]
	v_mov_b64_e32 v[8:9], v[74:75]
	s_waitcnt vmcnt(0)
	v_pk_add_f32 v[6:7], v[8:9], v[6:7]
	s_nop 0
	v_and_b32_e32 v9, 0x7fffffff, v7
	v_and_b32_e32 v8, 0x7fffffff, v6
	v_pk_fma_f32 v[8:9], v[8:9], s[54:55], 1.0 op_sel_hi:[1,0,0]
	v_cmp_gt_f32_e32 vcc, 0, v6
	v_rcp_f32_e32 v8, v8
	v_rcp_f32_e32 v9, v9
	s_nop 0
	v_pk_fma_f32 v[10:11], v[8:9], s[12:13], v[30:31] op_sel_hi:[1,0,0]
	s_nop 0
	v_pk_fma_f32 v[10:11], v[8:9], v[10:11], s[34:35] op_sel_hi:[1,1,0]
	s_nop 0
	v_pk_fma_f32 v[10:11], v[8:9], v[10:11], s[36:37] op_sel_hi:[1,1,0]
	s_nop 0
	v_pk_fma_f32 v[10:11], v[8:9], v[10:11], s[38:39] op_sel_hi:[1,1,0]
	s_nop 0
	v_pk_mul_f32 v[8:9], v[8:9], v[10:11]
	v_pk_mul_f32 v[10:11], v[6:7], v[6:7]
	s_nop 0
	v_pk_mul_f32 v[10:11], v[10:11], s[40:41] op_sel_hi:[1,0]
	s_nop 0
	v_exp_f32_e32 v10, v10
	v_exp_f32_e32 v11, v11
	s_nop 0
	v_pk_mul_f32 v[8:9], v[10:11], v[8:9]
	s_nop 0
	v_pk_mul_f32 v[10:11], v[6:7], v[8:9]
	v_pk_fma_f32 v[8:9], v[6:7], v[8:9], v[6:7] neg_lo:[1,0,0] neg_hi:[1,0,0]
	s_nop 0
	v_cndmask_b32_e32 v0, v8, v10, vcc
	v_cmp_gt_f32_e32 vcc, 0, v7
	v_lshlrev_b32_e32 v7, 16, v5
	v_and_b32_e32 v5, 0xffff0000, v5
	v_cndmask_b32_e32 v6, v9, v11, vcc
	v_mul_f32_e32 v0, v0, v7
	v_mul_f32_e32 v5, v6, v5
	v_cvt_pk_bf16_f32 v5, v0, v5
	v_lshl_or_b32 v0, v34, 6, v35
	v_mov_b64_e32 v[6:7], s[20:21]
	s_nop 0
	v_mad_i64_i32 v[6:7], s[12:13], v0, s18, v[6:7]
	s_lshr_b32 s12, s77, 6
	s_mul_i32 s12, s12, 0x2c0
	s_addk_i32 s12, 0xbf
	v_add_u32_e32 v0, 0x200, v33
	v_cmp_lt_i32_e32 vcc, s12, v33
	v_lshl_add_u64 v[6:7], v[6:7], 0, v[18:19]
	s_or_b64 s[10:11], vcc, s[10:11]
	v_mov_b32_e32 v33, v0
	global_store_dwordx4 v[6:7], v[2:5], off sc0 sc1
	s_andn2_b64 exec, exec, s[10:11]
	s_cbranch_execz .LBB0_804
